# noprio + loop-edge rotation: k-advance scalars hidden in last MFMA block (IN/OUT), attention slot updates moved before closing waits
# speedup vs baseline: 1.0100x; 1.0011x over previous
; #define WAIT_BAR(N) asm volatile("s_waitcnt vmcnt(" #N ") lgkmcnt(0)\n\ts_barrier" ::: "memory")
; #define RESC() do { if (!FIXM && resc) { asm volatile("s_waitcnt lgkmcnt(0)" ::: "memory"); \
;       _Pragma("unroll") for (int d_ = 0; d_ < 2; ++d_) _Pragma("unroll") for (int r = 0; r < 16; ++r) o[d_][r] *= wsf[crow(r, hi)]; } } while (0)
; #define ROT() do { sl_prev = sl_cur; sl_cur = sl_next; sl_next = (sl_next == (NSLOT - 1) * SLOTB) ? 0 : sl_next + SLOTB; } while (0)
; template <int THRL, bool FIXM> __device__ __forceinline__ bool attn_unit(const h16* Qrows, const h16* __restrict__ Kh, const h16* __restrict__ Vh, const int NT, h16* Yrows, const h16* BZrows, char* shm, const int tid, const float mfix, ...
;     ...
;     STEP(pB0, pB1, pA0, pA1, t, true, true, true);     WAIT_BAR(2); RESC(); ROT();
.LBB0_77:
	v_add_u32_e32 v0, s44, v233
	ds_read_b64_tr_b16 v[62:63], v0 offset:24576
	ds_read_b64_tr_b16 v[64:65], v0 offset:25088
	v_add_f32_e32 v51, v82, v83
	v_add_f32_e32 v51, v84, v51
	v_add_f32_e32 v51, v85, v51
	v_add_f32_e32 v51, v86, v51
	v_add_f32_e32 v51, v87, v51
	v_cvt_pk_f16_f32 v160, v82, v83
	v_cvt_pk_f16_f32 v161, v84, v85
	s_waitcnt lgkmcnt(9)
	v_mfma_f32_32x32x16_f16 v[114:129], v[192:195], v[144:147], v[2:17]
	ds_read_b64_tr_b16 v[82:83], v0 offset:28672
	ds_read_b64_tr_b16 v[84:85], v0 offset:29184
	v_add_f32_e32 v51, v88, v51
	v_add_f32_e32 v51, v89, v51
	v_add_f32_e32 v51, v90, v51
	v_add_f32_e32 v51, v91, v51
	v_cvt_pk_f16_f32 v162, v86, v87
	v_cvt_pk_f16_f32 v163, v88, v89
	s_waitcnt lgkmcnt(10)
	v_mfma_f32_32x32x16_f16 v[98:113], v[188:191], v[144:147], v[2:17]
	ds_read_b64_tr_b16 v[86:87], v0 offset:25600
	ds_read_b64_tr_b16 v[88:89], v0 offset:26112
	v_add_f32_e32 v51, v92, v51
	v_add_f32_e32 v51, v93, v51
	v_add_f32_e32 v51, v94, v51
	v_add_f32_e32 v51, v95, v51
	v_cvt_pk_f16_f32 v156, v90, v91
	v_cvt_pk_f16_f32 v157, v92, v93
	s_waitcnt lgkmcnt(11)
	v_mfma_f32_32x32x16_f16 v[114:129], v[184:187], v[140:143], v[114:129]
	ds_read_b64_tr_b16 v[90:91], v0 offset:29696
	ds_read_b64_tr_b16 v[92:93], v0 offset:30208
	v_add_f32_e32 v51, v96, v51
	v_add_f32_e32 v51, v97, v51
	v_add_f32_e32 v51, v66, v51
	v_add_f32_e32 v51, v67, v51
	v_cvt_pk_f16_f32 v158, v94, v95
	v_cvt_pk_f16_f32 v159, v96, v97
	s_waitcnt lgkmcnt(12)
	v_mfma_f32_32x32x16_f16 v[98:113], v[180:183], v[140:143], v[98:113]
	ds_read_b64_tr_b16 v[94:95], v0 offset:26624
	ds_read_b64_tr_b16 v[96:97], v0 offset:27136
	v_add_f32_e32 v51, v68, v51
	v_add_f32_e32 v51, v69, v51
	v_add_f32_e32 v51, v70, v51
	v_add_f32_e32 v51, v71, v51
	v_cvt_pk_f16_f32 v152, v66, v67
	v_cvt_pk_f16_f32 v153, v68, v69
	s_waitcnt lgkmcnt(13)
	v_mfma_f32_32x32x16_f16 v[114:129], v[176:179], v[136:139], v[114:129]
	ds_read_b64_tr_b16 v[66:67], v0 offset:30720
	ds_read_b64_tr_b16 v[68:69], v0 offset:31232
	v_add_f32_e32 v51, v72, v51
	v_add_f32_e32 v51, v73, v51
	v_add_f32_e32 v51, v74, v51
	v_add_f32_e32 v51, v75, v51
	v_cvt_pk_f16_f32 v154, v70, v71
	v_cvt_pk_f16_f32 v155, v72, v73
	s_waitcnt lgkmcnt(14)
	v_mfma_f32_32x32x16_f16 v[98:113], v[172:175], v[136:139], v[98:113]
	ds_read_b64_tr_b16 v[70:71], v0 offset:27648
	ds_read_b64_tr_b16 v[72:73], v0 offset:28160
	v_add_f32_e32 v51, v76, v51
	v_add_f32_e32 v51, v77, v51
	v_add_f32_e32 v51, v78, v51
	v_add_f32_e32 v51, v79, v51
	v_cvt_pk_f16_f32 v148, v74, v75
	v_cvt_pk_f16_f32 v149, v76, v77
	s_waitcnt lgkmcnt(14)
	v_mfma_f32_32x32x16_f16 v[114:129], v[168:171], v[132:135], v[114:129]
	ds_read_b64_tr_b16 v[74:75], v0 offset:31744
	ds_read_b64_tr_b16 v[76:77], v0 offset:32256
	v_add_f32_e32 v0, v80, v51
	v_add_f32_e32 v0, v81, v0
	v_add_f32_e32 v0, 0, v0
	v_cvt_pk_f16_f32 v150, v78, v79
	v_cvt_pk_f16_f32 v151, v80, v81
	v_mfma_f32_32x32x16_f16 v[98:113], v[164:167], v[132:135], v[98:113]
	v_lshl_add_u64 v[58:59], v[56:57], 0, s[2:3]
	v_add_f32_e32 v0, v50, v0
	v_lshl_add_u64 v[50:51], v[58:59], 0, s[46:47]
	s_add_i32 s43, s42, s97
	s_mov_b32 s44, m0
	s_mov_b32 m0, s43
	s_nop 0
	global_load_lds_dwordx4 v[50:51], off
	s_mov_b32 m0, s44
	v_lshl_add_u64 v[60:61], v[54:55], 0, s[2:3]
	v_lshl_add_u64 v[50:51], v[60:61], 0, s[36:37]
	s_add_i32 s43, s25, s83
	s_mov_b32 s44, m0
	s_mov_b32 m0, s43
	s_nop 0
	global_load_lds_dwordx4 v[50:51], off
	s_mov_b32 m0, s44
	s_waitcnt lgkmcnt(14)
	v_mfma_f32_32x32x16_f16 v[18:33], v[160:163], v[62:65], v[18:33]
	v_exp_f32_e32 v114, v114
	v_exp_f32_e32 v115, v115
	v_exp_f32_e32 v116, v116
	v_exp_f32_e32 v117, v117
	s_waitcnt lgkmcnt(12)
	v_mfma_f32_32x32x16_f16 v[34:49], v[160:163], v[82:85], v[34:49]
	v_exp_f32_e32 v118, v118
	v_exp_f32_e32 v119, v119
	v_exp_f32_e32 v120, v120
	v_exp_f32_e32 v121, v121
	v_add_u32_e32 v50, s25, v219
	ds_read_b128 v[62:65], v50
	ds_read_b128 v[164:167], v50 offset:512
	s_waitcnt lgkmcnt(12)
	v_mfma_f32_32x32x16_f16 v[18:33], v[156:159], v[86:89], v[18:33]
	v_exp_f32_e32 v122, v122
	v_exp_f32_e32 v123, v123
	v_exp_f32_e32 v124, v124
	v_exp_f32_e32 v125, v125
	ds_read_b128 v[168:171], v50 offset:2048
	ds_read_b128 v[172:175], v50 offset:2560
	s_waitcnt lgkmcnt(12)
	v_mfma_f32_32x32x16_f16 v[34:49], v[156:159], v[90:93], v[34:49]
	v_exp_f32_e32 v126, v126
	v_exp_f32_e32 v127, v127
	v_exp_f32_e32 v128, v128
	v_exp_f32_e32 v129, v129
	ds_read_b128 v[176:179], v50 offset:4096
	ds_read_b128 v[180:183], v50 offset:4608
	s_waitcnt lgkmcnt(12)
	v_mfma_f32_32x32x16_f16 v[18:33], v[152:155], v[94:97], v[18:33]
	v_exp_f32_e32 v98, v98
	v_exp_f32_e32 v99, v99
	v_exp_f32_e32 v100, v100
	v_exp_f32_e32 v101, v101
	ds_read_b128 v[184:187], v50 offset:6144
	ds_read_b128 v[50:53], v50 offset:6656
	s_waitcnt lgkmcnt(12)
	v_mfma_f32_32x32x16_f16 v[34:49], v[152:155], v[66:69], v[34:49]
	v_exp_f32_e32 v102, v102
	v_exp_f32_e32 v103, v103
	v_exp_f32_e32 v104, v104
	v_exp_f32_e32 v105, v105
	s_waitcnt lgkmcnt(10)
	v_mfma_f32_32x32x16_f16 v[18:33], v[148:151], v[70:73], v[18:33]
	v_exp_f32_e32 v106, v106
	v_exp_f32_e32 v107, v107
	v_exp_f32_e32 v108, v108
	v_exp_f32_e32 v109, v109
	s_waitcnt lgkmcnt(8)
	v_mfma_f32_32x32x16_f16 v[34:49], v[148:151], v[74:77], v[34:49]
	v_exp_f32_e32 v110, v110
	v_exp_f32_e32 v111, v111
	v_exp_f32_e32 v112, v112
	v_exp_f32_e32 v113, v113
	s_add_i32 s43, s25, 0x2000
	s_cmpk_lg_i32 s25, 0x4000
	s_cselect_b32 s43, s43, 0
	s_waitcnt vmcnt(2) lgkmcnt(0)
	s_barrier
; #define WAIT_BAR(N) asm volatile("s_waitcnt vmcnt(" #N ") lgkmcnt(0)\n\ts_barrier" ::: "memory")
; #define RESC() do { if (!FIXM && resc) { asm volatile("s_waitcnt lgkmcnt(0)" ::: "memory"); \
;       _Pragma("unroll") for (int d_ = 0; d_ < 2; ++d_) _Pragma("unroll") for (int r = 0; r < 16; ++r) o[d_][r] *= wsf[crow(r, hi)]; } } while (0)
; #define ROT() do { sl_prev = sl_cur; sl_cur = sl_next; sl_next = (sl_next == (NSLOT - 1) * SLOTB) ? 0 : sl_next + SLOTB; } while (0)
; template <int THRL, bool FIXM> __device__ __forceinline__ bool attn_unit(const h16* Qrows, const h16* __restrict__ Kh, const h16* __restrict__ Vh, const int NT, h16* Yrows, const h16* BZrows, char* shm, const int tid, const float mfix, ...
;     ...
;   int t = 1;
;   for (; t + 5 < NT; t += 2) {
;     STEP(pB0, pB1, pA0, pA1, t, true, true, true);     WAIT_BAR(2); RESC(); ROT();
;     STEP(pA0, pA1, pB0, pB1, t + 1, true, true, true); WAIT_BAR(2); RESC(); ROT();
;   }
	v_add_u32_e32 v192, s42, v233
	ds_read_b64_tr_b16 v[188:189], v192 offset:24576
	ds_read_b64_tr_b16 v[190:191], v192 offset:25088
	s_waitcnt lgkmcnt(9)
	v_mfma_f32_32x32x16_f16 v[82:97], v[62:65], v[144:147], v[2:17]
	v_add_f32_e32 v66, v114, v115
	v_add_f32_e32 v66, v116, v66
	v_add_f32_e32 v66, v117, v66
	v_add_f32_e32 v66, v118, v66
	v_add_f32_e32 v66, v119, v66
	v_cvt_pk_f16_f32 v160, v114, v115
	v_cvt_pk_f16_f32 v161, v116, v117
	ds_read_b64_tr_b16 v[62:63], v192 offset:28672
	ds_read_b64_tr_b16 v[64:65], v192 offset:29184
	v_add_f32_e32 v66, v120, v66
	v_add_f32_e32 v66, v121, v66
	v_add_f32_e32 v66, v122, v66
	v_add_f32_e32 v148, v123, v66
	s_waitcnt lgkmcnt(10)
	v_mfma_f32_32x32x16_f16 v[66:81], v[164:167], v[144:147], v[2:17]
	v_cvt_pk_f16_f32 v162, v118, v119
	v_cvt_pk_f16_f32 v163, v120, v121
	ds_read_b64_tr_b16 v[114:115], v192 offset:25600
	ds_read_b64_tr_b16 v[116:117], v192 offset:26112
	s_waitcnt lgkmcnt(11)
	v_mfma_f32_32x32x16_f16 v[82:97], v[168:171], v[140:143], v[82:97]
	v_add_f32_e32 v118, v124, v148
	v_add_f32_e32 v118, v125, v118
	v_add_f32_e32 v118, v126, v118
	v_add_f32_e32 v148, v127, v118
	v_cvt_pk_f16_f32 v156, v122, v123
	v_cvt_pk_f16_f32 v157, v124, v125
	ds_read_b64_tr_b16 v[118:119], v192 offset:29696
	ds_read_b64_tr_b16 v[120:121], v192 offset:30208
	s_waitcnt lgkmcnt(12)
	v_mfma_f32_32x32x16_f16 v[66:81], v[172:175], v[140:143], v[66:81]
	v_add_f32_e32 v122, v128, v148
	v_add_f32_e32 v122, v129, v122
	v_add_f32_e32 v122, v98, v122
	v_add_f32_e32 v148, v99, v122
	v_cvt_pk_f16_f32 v158, v126, v127
	v_cvt_pk_f16_f32 v159, v128, v129
	ds_read_b64_tr_b16 v[122:123], v192 offset:26624
	ds_read_b64_tr_b16 v[124:125], v192 offset:27136
	s_waitcnt lgkmcnt(13)
	v_mfma_f32_32x32x16_f16 v[82:97], v[176:179], v[136:139], v[82:97]
	v_add_f32_e32 v126, v100, v148
	v_add_f32_e32 v126, v101, v126
	v_add_f32_e32 v126, v102, v126
	v_add_f32_e32 v126, v103, v126
	v_cvt_pk_f16_f32 v152, v98, v99
	v_cvt_pk_f16_f32 v153, v100, v101
	ds_read_b64_tr_b16 v[98:99], v192 offset:30720
	ds_read_b64_tr_b16 v[100:101], v192 offset:31232
	s_waitcnt lgkmcnt(14)
	v_mfma_f32_32x32x16_f16 v[66:81], v[180:183], v[136:139], v[66:81]
	v_add_f32_e32 v126, v104, v126
	v_add_f32_e32 v126, v105, v126
	v_add_f32_e32 v126, v106, v126
	v_add_f32_e32 v126, v107, v126
	v_cvt_pk_f16_f32 v154, v102, v103
	v_cvt_pk_f16_f32 v155, v104, v105
	ds_read_b64_tr_b16 v[102:103], v192 offset:27648
	ds_read_b64_tr_b16 v[104:105], v192 offset:28160
	s_waitcnt lgkmcnt(14)
	v_mfma_f32_32x32x16_f16 v[82:97], v[184:187], v[132:135], v[82:97]
	v_add_f32_e32 v126, v108, v126
	v_add_f32_e32 v126, v109, v126
	v_add_f32_e32 v126, v110, v126
	v_add_f32_e32 v126, v111, v126
	v_cvt_pk_f16_f32 v148, v106, v107
	v_cvt_pk_f16_f32 v149, v108, v109
	ds_read_b64_tr_b16 v[106:107], v192 offset:31744
	ds_read_b64_tr_b16 v[108:109], v192 offset:32256
	v_mfma_f32_32x32x16_f16 v[66:81], v[50:53], v[132:135], v[66:81]
	v_add_f32_e32 v50, v112, v126
	v_add_f32_e32 v50, v113, v50
	v_add_f32_e32 v50, 0, v50
	v_cvt_pk_f16_f32 v150, v110, v111
	v_cvt_pk_f16_f32 v151, v112, v113
	v_lshl_add_u64 v[52:53], v[58:59], 0, s[48:49]
	s_add_i32 s42, s25, s97
	s_mov_b32 s44, m0
	s_mov_b32 m0, s42
	s_nop 0
	global_load_lds_dwordx4 v[52:53], off
	s_mov_b32 m0, s44
	v_lshl_add_u64 v[52:53], v[60:61], 0, s[52:53]
	s_add_i32 s42, s43, s83
	s_mov_b32 s44, m0
	s_mov_b32 m0, s42
	s_nop 0
	global_load_lds_dwordx4 v[52:53], off
	s_mov_b32 m0, s44
	v_add_f32_e32 v50, v0, v50
	s_waitcnt lgkmcnt(14)
	v_mfma_f32_32x32x16_f16 v[18:33], v[160:163], v[188:191], v[18:33]
	v_exp_f32_e32 v82, v82
	v_exp_f32_e32 v83, v83
	v_exp_f32_e32 v84, v84
	v_exp_f32_e32 v85, v85
	s_waitcnt lgkmcnt(12)
	v_mfma_f32_32x32x16_f16 v[34:49], v[160:163], v[62:65], v[34:49]
	v_exp_f32_e32 v86, v86
	v_exp_f32_e32 v87, v87
	v_exp_f32_e32 v88, v88
	v_exp_f32_e32 v89, v89
	v_add_u32_e32 v0, s43, v219
	ds_read_b128 v[192:195], v0
	ds_read_b128 v[188:191], v0 offset:512
	s_waitcnt lgkmcnt(12)
	v_mfma_f32_32x32x16_f16 v[18:33], v[156:159], v[114:117], v[18:33]
	v_exp_f32_e32 v90, v90
	v_exp_f32_e32 v91, v91
	v_exp_f32_e32 v92, v92
	v_exp_f32_e32 v93, v93
	ds_read_b128 v[184:187], v0 offset:2048
	ds_read_b128 v[180:183], v0 offset:2560
	s_waitcnt lgkmcnt(12)
	v_mfma_f32_32x32x16_f16 v[34:49], v[156:159], v[118:121], v[34:49]
	v_exp_f32_e32 v94, v94
	v_exp_f32_e32 v95, v95
	v_exp_f32_e32 v96, v96
	v_exp_f32_e32 v97, v97
	ds_read_b128 v[176:179], v0 offset:4096
	ds_read_b128 v[172:175], v0 offset:4608
	s_waitcnt lgkmcnt(12)
	v_mfma_f32_32x32x16_f16 v[18:33], v[152:155], v[122:125], v[18:33]
	v_exp_f32_e32 v66, v66
	v_exp_f32_e32 v67, v67
	v_exp_f32_e32 v68, v68
	v_exp_f32_e32 v69, v69
	ds_read_b128 v[168:171], v0 offset:6144
	ds_read_b128 v[164:167], v0 offset:6656
	s_waitcnt lgkmcnt(12)
	v_mfma_f32_32x32x16_f16 v[34:49], v[152:155], v[98:101], v[34:49]
	v_exp_f32_e32 v70, v70
	v_exp_f32_e32 v71, v71
	v_exp_f32_e32 v72, v72
	v_exp_f32_e32 v73, v73
	s_waitcnt lgkmcnt(10)
	v_mfma_f32_32x32x16_f16 v[18:33], v[148:151], v[102:105], v[18:33]
	v_exp_f32_e32 v74, v74
	v_exp_f32_e32 v75, v75
	v_exp_f32_e32 v76, v76
	v_exp_f32_e32 v77, v77
	s_waitcnt lgkmcnt(8)
	v_mfma_f32_32x32x16_f16 v[34:49], v[148:151], v[106:109], v[34:49]
	v_exp_f32_e32 v78, v78
	v_exp_f32_e32 v79, v79
	v_exp_f32_e32 v80, v80
	v_exp_f32_e32 v81, v81
	s_add_i32 s45, s43, 0x2000
	s_cmpk_lg_i32 s43, 0x4000
	s_mov_b32 s44, s25
	s_cselect_b32 s25, s45, 0
	s_add_i32 s24, s24, 2
	v_lshl_add_u64 v[54:55], v[54:55], 0, s[62:63]
	v_lshl_add_u64 v[56:57], v[56:57], 0, s[62:63]
	s_mov_b32 s42, s43
	s_cmp_lt_u32 s24, 29
	s_waitcnt vmcnt(2) lgkmcnt(0)
	s_barrier
	s_cbranch_scc1 .LBB0_77
	s_mov_b64 s[36:37], 0x10c84000
	s_mov_b64 s[60:61], 0x10388000
	s_mov_b32 s45, 31
	s_branch .LBB0_80

; #define PG8_STAGE(bufoff, gbase) do { _Pragma("unroll") for (int _i = 0; _i < 2; ++_i) \
;         __builtin_amdgcn_global_load_lds((const unsigned*)((const char*)(gbase) + voffA[_i]), (LAS unsigned*)(lds + (bufoff) + ldsw + _i * 8192), 16, 0, 0); } while (0)
; #define PG8_LDA(dst, b, h) do { _Pragma("unroll") for (int m = 0; m < 4; ++m) _Pragma("unroll") for (int k = 0; k < 2; ++k) dst[m][k] = *(const LAS h16x8*)(lds + PG8_SA(b, h) + aoff + m * 2048 + k * 1024); } while (0)
; #define PG8_LDB(dst, b, h) do { _Pragma("unroll") for (int n = 0; n < 2; ++n) _Pragma("unroll") for (int k = 0; k < 2; ++k) dst[n][k] = *(const LAS h16x8*)(lds + PG8_SB(b, h) + boff + n * 2048 + k * 1024); } while (0)
; #define PG8_LDA1(dst, b) do { if constexpr (!HALFM) PG8_LDA(dst, b, 1); } while (0)
; #define PG8_MMA1(At, B0, B1) do { if constexpr (!HALFM) { PG8_MMA(1, 0, At, B0); PG8_MMA(1, 1, At, B1); } } while (0)
; #define PG8_WAIT_V(n) asm volatile("s_waitcnt vmcnt(" #n ")" ::: "memory")
; #define PG8_WAIT_L(n) asm volatile("s_waitcnt lgkmcnt(" #n ")" ::: "memory")
; #define PG8_BAR __builtin_amdgcn_s_barrier()
; #define PG8_SCHED __builtin_amdgcn_sched_barrier(0)
; template <class Epi, bool ALIGN_EPI, bool SP2, bool BF = false, bool HALFM = false, class Order = StaticOrder>
; __device__ __forceinline__ void gemm_phase(LAS unsigned char* lds, const int tid, const Gemm g, const Order& S, const Epi& E, const bool dry = false) {
;     ...
;             if constexpr (SP2) {
;             PG8_LDB(B0, 0, 0); PG8_LDB(B1, 0, 1); PG8_SCHED; PG8_LDA(At, 0, 0); PG8_STAGE(PG8_SA(1, 1), a1 + hstep);
;             PG8_WAIT_V(8); PG8_WAIT_L(0); PG8_BAR; PG8_MMA(0, 0, At, B0); PG8_MMA(0, 1, At, B1); PG8_BAR; PG8_SCHED;
;             PG8_LDA1(At, 0); PG8_STAGE(PG8_SB(0, 0), b2); PG8_STAGE(PG8_SB(0, 1), b2 + hstep); PG8_STAGE(PG8_SA(0, 0), a2);
;             PG8_WAIT_V(8); PG8_WAIT_L(0); PG8_BAR; PG8_MMA1(At, B0, B1); PG8_BAR; PG8_SCHED;
.LBB0_452:
	v_add_u32_e32 v0, s52, v189
	ds_read_b128 v[18:21], v0
	ds_read_b128 v[22:25], v0 offset:1024
	ds_read_b128 v[26:29], v0 offset:2048
	ds_read_b128 v[30:33], v0 offset:3072
	v_add_u32_e32 v0, s55, v189
	ds_read_b128 v[50:53], v0
	ds_read_b128 v[54:57], v0 offset:1024
	ds_read_b128 v[58:61], v0 offset:2048
	ds_read_b128 v[62:65], v0 offset:3072
	s_add_u32 s38, s2, 0xfffc0080
	s_addc_u32 s39, s3, -1
	s_cmp_eq_u32 s97, 12
	s_cselect_b32 s43, s1, s39
	s_cselect_b32 s42, s5, s38
	s_cselect_b32 s39, s19, s45
	s_cselect_b32 s38, s21, s44
	v_lshl_add_u64 v[222:223], s[2:3], 0, v[168:169]
	s_add_i32 m0, s79, 0xc000
	ds_read_b128 v[172:175], v190
	ds_read_b128 v[176:179], v190 offset:1024
	ds_read_b128 v[192:195], v190 offset:2048
	ds_read_b128 v[196:199], v190 offset:3072
	ds_read_b128 v[200:203], v190 offset:4096
	ds_read_b128 v[204:207], v190 offset:5120
	ds_read_b128 v[214:217], v190 offset:6144
	ds_read_b128 v[218:221], v190 offset:7168
	global_load_lds_dwordx4 v[222:223], off
	v_lshl_add_u64 v[222:223], s[2:3], 0, v[170:171]
	s_add_i32 m0, s79, 0xe000
	s_nop 0
	global_load_lds_dwordx4 v[222:223], off
	s_waitcnt vmcnt(8)
	s_waitcnt lgkmcnt(0)
	s_barrier
	s_waitcnt lgkmcnt(0)
	v_mfma_f32_16x16x32_f16 v[160:163], v[18:21], v[172:175], v[160:163]
	v_mfma_f32_16x16x32_f16 v[156:159], v[26:29], v[172:175], v[156:159]
	v_mfma_f32_16x16x32_f16 v[144:147], v[18:21], v[192:195], v[144:147]
	v_mfma_f32_16x16x32_f16 v[140:143], v[26:29], v[192:195], v[140:143]
	v_mfma_f32_16x16x32_f16 v[126:129], v[18:21], v[200:203], v[126:129]
	v_mfma_f32_16x16x32_f16 v[122:125], v[26:29], v[200:203], v[122:125]
	v_mfma_f32_16x16x32_f16 v[110:113], v[18:21], v[214:217], v[110:113]
	v_mfma_f32_16x16x32_f16 v[106:109], v[26:29], v[214:217], v[106:109]
	v_mfma_f32_16x16x32_f16 v[160:163], v[22:25], v[176:179], v[160:163]
	v_mfma_f32_16x16x32_f16 v[156:159], v[30:33], v[176:179], v[156:159]
	v_mfma_f32_16x16x32_f16 v[144:147], v[22:25], v[196:199], v[144:147]
	v_mfma_f32_16x16x32_f16 v[140:143], v[30:33], v[196:199], v[140:143]
	v_mfma_f32_16x16x32_f16 v[126:129], v[22:25], v[204:207], v[126:129]
	v_mfma_f32_16x16x32_f16 v[122:125], v[30:33], v[204:207], v[122:125]
	v_mfma_f32_16x16x32_f16 v[110:113], v[22:25], v[218:221], v[110:113]
	v_mfma_f32_16x16x32_f16 v[106:109], v[30:33], v[218:221], v[106:109]
	v_mfma_f32_16x16x32_f16 v[152:155], v[50:53], v[172:175], v[152:155]
	v_mfma_f32_16x16x32_f16 v[148:151], v[58:61], v[172:175], v[148:151]
	v_mfma_f32_16x16x32_f16 v[136:139], v[50:53], v[192:195], v[136:139]
	v_mfma_f32_16x16x32_f16 v[132:135], v[58:61], v[192:195], v[132:135]
	v_mfma_f32_16x16x32_f16 v[118:121], v[50:53], v[200:203], v[118:121]
	v_mfma_f32_16x16x32_f16 v[114:117], v[58:61], v[200:203], v[114:117]
	v_mfma_f32_16x16x32_f16 v[102:105], v[50:53], v[214:217], v[102:105]
	v_mfma_f32_16x16x32_f16 v[98:101], v[58:61], v[214:217], v[98:101]
	v_mfma_f32_16x16x32_f16 v[152:155], v[54:57], v[176:179], v[152:155]
	v_mfma_f32_16x16x32_f16 v[148:151], v[62:65], v[176:179], v[148:151]
	v_mfma_f32_16x16x32_f16 v[136:139], v[54:57], v[196:199], v[136:139]
	v_mfma_f32_16x16x32_f16 v[132:135], v[62:65], v[196:199], v[132:135]
	v_mfma_f32_16x16x32_f16 v[118:121], v[54:57], v[204:207], v[118:121]
	v_mfma_f32_16x16x32_f16 v[114:117], v[62:65], v[204:207], v[114:117]
	v_mfma_f32_16x16x32_f16 v[102:105], v[54:57], v[218:221], v[102:105]
	v_mfma_f32_16x16x32_f16 v[98:101], v[62:65], v[218:221], v[98:101]
	s_barrier
	s_mov_b32 m0, s53
	v_lshl_add_u64 v[226:227], s[38:39], 0, v[164:165]
	s_add_u32 vcc_lo, s38, 0x40000
	ds_read_b128 v[172:175], v190 offset:16384
	ds_read_b128 v[176:179], v190 offset:17408
	ds_read_b128 v[192:195], v190 offset:18432
	ds_read_b128 v[196:199], v190 offset:19456
	ds_read_b128 v[200:203], v190 offset:20480
	ds_read_b128 v[204:207], v190 offset:21504
	ds_read_b128 v[214:217], v190 offset:22528
	ds_read_b128 v[218:221], v190 offset:23552
	global_load_lds_dwordx4 v[226:227], off
	v_lshl_add_u64 v[238:239], s[38:39], 0, v[166:167]
	s_mov_b32 m0, s54
	s_addc_u32 vcc_hi, s39, 0
	global_load_lds_dwordx4 v[238:239], off
	v_lshl_add_u64 v[222:223], vcc, 0, v[164:165]
	s_mov_b32 m0, s77
	v_lshl_add_u64 v[248:249], s[42:43], 0, v[164:165]
	global_load_lds_dwordx4 v[222:223], off
	v_lshl_add_u64 v[222:223], vcc, 0, v[166:167]
	s_mov_b32 m0, s78
	v_lshl_add_u64 v[210:211], s[42:43], 0, v[166:167]
	global_load_lds_dwordx4 v[222:223], off
	s_mov_b32 m0, s79
	s_nop 0
	global_load_lds_dwordx4 v[248:249], off
	s_mov_b32 m0, s80
	s_nop 0
	global_load_lds_dwordx4 v[210:211], off
	s_waitcnt vmcnt(8)
	s_waitcnt lgkmcnt(0)
	s_barrier
; #define PG8_STAGE(bufoff, gbase) do { _Pragma("unroll") for (int _i = 0; _i < 2; ++_i) \
;         __builtin_amdgcn_global_load_lds((const unsigned*)((const char*)(gbase) + voffA[_i]), (LAS unsigned*)(lds + (bufoff) + ldsw + _i * 8192), 16, 0, 0); } while (0)
; #define PG8_LDA(dst, b, h) do { _Pragma("unroll") for (int m = 0; m < 4; ++m) _Pragma("unroll") for (int k = 0; k < 2; ++k) dst[m][k] = *(const LAS h16x8*)(lds + PG8_SA(b, h) + aoff + m * 2048 + k * 1024); } while (0)
; #define PG8_LDB(dst, b, h) do { _Pragma("unroll") for (int n = 0; n < 2; ++n) _Pragma("unroll") for (int k = 0; k < 2; ++k) dst[n][k] = *(const LAS h16x8*)(lds + PG8_SB(b, h) + boff + n * 2048 + k * 1024); } while (0)
; #define PG8_MMA1(At, B0, B1) do { if constexpr (!HALFM) { PG8_MMA(1, 0, At, B0); PG8_MMA(1, 1, At, B1); } } while (0)
; #define PG8_WAIT_V(n) asm volatile("s_waitcnt vmcnt(" #n ")" ::: "memory")
; #define PG8_WAIT_L(n) asm volatile("s_waitcnt lgkmcnt(" #n ")" ::: "memory")
; #define PG8_BAR __builtin_amdgcn_s_barrier()
; #define PG8_SCHED __builtin_amdgcn_sched_barrier(0)
; template <class Epi, bool ALIGN_EPI, bool SP2, bool BF = false, bool HALFM = false, class Order = StaticOrder>
; __device__ __forceinline__ void gemm_phase(LAS unsigned char* lds, const int tid, const Gemm g, const Order& S, const Epi& E, const bool dry = false) {
;     ...
;             PG8_WAIT_V(8); PG8_WAIT_L(0); PG8_BAR; PG8_MMA1(At, B0, B1); PG8_BAR; PG8_SCHED;
;             PG8_LDB(B0, 1, 0); PG8_LDB(B1, 1, 1); PG8_SCHED; PG8_LDA(At, 1, 0); PG8_STAGE(PG8_SA(0, 1), a2 + hstep);
;             PG8_WAIT_V(8); PG8_WAIT_L(0); PG8_BAR; PG8_MMA(0, 0, At, B0); PG8_MMA(0, 1, At, B1); PG8_BAR; PG8_SCHED;
	s_waitcnt lgkmcnt(0)
	v_mfma_f32_16x16x32_f16 v[94:97], v[18:21], v[172:175], v[94:97]
	v_mfma_f32_16x16x32_f16 v[90:93], v[26:29], v[172:175], v[90:93]
	v_mfma_f32_16x16x32_f16 v[78:81], v[18:21], v[192:195], v[78:81]
	v_mfma_f32_16x16x32_f16 v[74:77], v[26:29], v[192:195], v[74:77]
	v_mfma_f32_16x16x32_f16 v[46:49], v[18:21], v[200:203], v[46:49]
	v_mfma_f32_16x16x32_f16 v[42:45], v[26:29], v[200:203], v[42:45]
	v_mfma_f32_16x16x32_f16 v[14:17], v[18:21], v[214:217], v[14:17]
	v_mfma_f32_16x16x32_f16 v[10:13], v[26:29], v[214:217], v[10:13]
	v_mfma_f32_16x16x32_f16 v[94:97], v[22:25], v[176:179], v[94:97]
	v_mfma_f32_16x16x32_f16 v[90:93], v[30:33], v[176:179], v[90:93]
	v_mfma_f32_16x16x32_f16 v[78:81], v[22:25], v[196:199], v[78:81]
	v_mfma_f32_16x16x32_f16 v[74:77], v[30:33], v[196:199], v[74:77]
	v_mfma_f32_16x16x32_f16 v[46:49], v[22:25], v[204:207], v[46:49]
	v_mfma_f32_16x16x32_f16 v[42:45], v[30:33], v[204:207], v[42:45]
	v_mfma_f32_16x16x32_f16 v[14:17], v[22:25], v[218:221], v[14:17]
	v_mfma_f32_16x16x32_f16 v[10:13], v[30:33], v[218:221], v[10:13]
	v_mfma_f32_16x16x32_f16 v[38:41], v[50:53], v[200:203], v[38:41]
	v_mfma_f32_16x16x32_f16 v[34:37], v[58:61], v[200:203], v[34:37]
	v_mfma_f32_16x16x32_f16 v[6:9], v[50:53], v[214:217], v[6:9]
	v_mfma_f32_16x16x32_f16 v[2:5], v[58:61], v[214:217], v[2:5]
	v_mfma_f32_16x16x32_f16 v[18:21], v[50:53], v[172:175], v[86:89]
	v_mfma_f32_16x16x32_f16 v[22:25], v[58:61], v[172:175], v[82:85]
	v_mfma_f32_16x16x32_f16 v[26:29], v[50:53], v[192:195], v[70:73]
	v_mfma_f32_16x16x32_f16 v[30:33], v[58:61], v[192:195], v[66:69]
	v_mfma_f32_16x16x32_f16 v[38:41], v[54:57], v[204:207], v[38:41]
	v_mfma_f32_16x16x32_f16 v[34:37], v[62:65], v[204:207], v[34:37]
	v_mfma_f32_16x16x32_f16 v[6:9], v[54:57], v[218:221], v[6:9]
	v_mfma_f32_16x16x32_f16 v[2:5], v[62:65], v[218:221], v[2:5]
	v_mfma_f32_16x16x32_f16 v[18:21], v[54:57], v[176:179], v[18:21]
	v_mfma_f32_16x16x32_f16 v[22:25], v[62:65], v[176:179], v[22:25]
	v_mfma_f32_16x16x32_f16 v[26:29], v[54:57], v[196:199], v[26:29]
	v_mfma_f32_16x16x32_f16 v[30:33], v[62:65], v[196:199], v[30:33]
	s_barrier
	v_add_u32_e32 v0, s85, v189
	ds_read_b128 v[50:53], v0
	ds_read_b128 v[54:57], v0 offset:1024
	ds_read_b128 v[58:61], v0 offset:2048
	ds_read_b128 v[62:65], v0 offset:3072
	v_add_u32_e32 v0, s51, v189
	ds_read_b128 v[172:175], v0
	ds_read_b128 v[176:179], v0 offset:1024
	ds_read_b128 v[192:195], v0 offset:2048
	ds_read_b128 v[196:199], v0 offset:3072
	s_add_u32 s42, s42, 0x40000
	s_addc_u32 s43, s43, 0
	s_mov_b32 m0, s81
	v_lshl_add_u64 v[222:223], s[42:43], 0, v[164:165]
	ds_read_b128 v[66:69], v190 offset:32768
	ds_read_b128 v[70:73], v190 offset:33792
	ds_read_b128 v[82:85], v190 offset:34816
	ds_read_b128 v[86:89], v190 offset:35840
	ds_read_b128 v[200:203], v190 offset:36864
	ds_read_b128 v[204:207], v190 offset:37888
	ds_read_b128 v[214:217], v190 offset:38912
	ds_read_b128 v[218:221], v190 offset:39936
	global_load_lds_dwordx4 v[222:223], off
	v_lshl_add_u64 v[222:223], s[42:43], 0, v[166:167]
	s_mov_b32 m0, s82
	s_nop 0
	global_load_lds_dwordx4 v[222:223], off
	s_waitcnt vmcnt(8)
	s_waitcnt lgkmcnt(0)
	s_barrier
	s_waitcnt lgkmcnt(0)
	v_mfma_f32_16x16x32_f16 v[160:163], v[50:53], v[66:69], v[160:163]
	v_mfma_f32_16x16x32_f16 v[156:159], v[58:61], v[66:69], v[156:159]
	v_mfma_f32_16x16x32_f16 v[144:147], v[50:53], v[82:85], v[144:147]
	v_mfma_f32_16x16x32_f16 v[140:143], v[58:61], v[82:85], v[140:143]
	v_mfma_f32_16x16x32_f16 v[126:129], v[50:53], v[200:203], v[126:129]
	v_mfma_f32_16x16x32_f16 v[122:125], v[58:61], v[200:203], v[122:125]
	v_mfma_f32_16x16x32_f16 v[110:113], v[50:53], v[214:217], v[110:113]
	v_mfma_f32_16x16x32_f16 v[106:109], v[58:61], v[214:217], v[106:109]
	v_mfma_f32_16x16x32_f16 v[160:163], v[54:57], v[70:73], v[160:163]
	v_mfma_f32_16x16x32_f16 v[156:159], v[62:65], v[70:73], v[156:159]
	v_mfma_f32_16x16x32_f16 v[144:147], v[54:57], v[86:89], v[144:147]
	v_mfma_f32_16x16x32_f16 v[140:143], v[62:65], v[86:89], v[140:143]
	v_mfma_f32_16x16x32_f16 v[126:129], v[54:57], v[204:207], v[126:129]
	v_mfma_f32_16x16x32_f16 v[122:125], v[62:65], v[204:207], v[122:125]
	v_mfma_f32_16x16x32_f16 v[110:113], v[54:57], v[218:221], v[110:113]
	v_mfma_f32_16x16x32_f16 v[106:109], v[62:65], v[218:221], v[106:109]
	v_mfma_f32_16x16x32_f16 v[152:155], v[172:175], v[66:69], v[152:155]
	v_mfma_f32_16x16x32_f16 v[66:69], v[192:195], v[66:69], v[148:151]
	v_mfma_f32_16x16x32_f16 v[148:151], v[196:199], v[70:73], v[66:69]
	v_mfma_f32_16x16x32_f16 v[66:69], v[172:175], v[82:85], v[136:139]
	v_mfma_f32_16x16x32_f16 v[136:139], v[176:179], v[86:89], v[66:69]
	v_mfma_f32_16x16x32_f16 v[66:69], v[192:195], v[82:85], v[132:135]
	v_mfma_f32_16x16x32_f16 v[132:135], v[196:199], v[86:89], v[66:69]
	v_mfma_f32_16x16x32_f16 v[66:69], v[172:175], v[200:203], v[118:121]
	v_mfma_f32_16x16x32_f16 v[118:121], v[176:179], v[204:207], v[66:69]
	v_mfma_f32_16x16x32_f16 v[66:69], v[192:195], v[200:203], v[114:117]
	v_mfma_f32_16x16x32_f16 v[114:117], v[196:199], v[204:207], v[66:69]
	v_mfma_f32_16x16x32_f16 v[66:69], v[172:175], v[214:217], v[102:105]
	v_mfma_f32_16x16x32_f16 v[102:105], v[176:179], v[218:221], v[66:69]
	v_mfma_f32_16x16x32_f16 v[66:69], v[192:195], v[214:217], v[98:101]
	v_mfma_f32_16x16x32_f16 v[152:155], v[176:179], v[70:73], v[152:155]
	v_mfma_f32_16x16x32_f16 v[98:101], v[196:199], v[218:221], v[66:69]
	s_barrier
; #define PG8_STAGE(bufoff, gbase) do { _Pragma("unroll") for (int _i = 0; _i < 2; ++_i) \
;         __builtin_amdgcn_global_load_lds((const unsigned*)((const char*)(gbase) + voffA[_i]), (LAS unsigned*)(lds + (bufoff) + ldsw + _i * 8192), 16, 0, 0); } while (0)
; #define PG8_LDA1(dst, b) do { if constexpr (!HALFM) PG8_LDA(dst, b, 1); } while (0)
; #define PG8_MMA1(At, B0, B1) do { if constexpr (!HALFM) { PG8_MMA(1, 0, At, B0); PG8_MMA(1, 1, At, B1); } } while (0)
; #define PG8_WAIT_V(n) asm volatile("s_waitcnt vmcnt(" #n ")" ::: "memory")
; #define PG8_WAIT_L(n) asm volatile("s_waitcnt lgkmcnt(" #n ")" ::: "memory")
; #define PG8_BAR __builtin_amdgcn_s_barrier()
; #define PG8_SCHED __builtin_amdgcn_sched_barrier(0)
; template <class Epi, bool ALIGN_EPI, bool SP2, bool BF = false, bool HALFM = false, class Order = StaticOrder>
; __device__ __forceinline__ void gemm_phase(LAS unsigned char* lds, const int tid, const Gemm g, const Order& S, const Epi& E, const bool dry = false) {
;     ...
;             PG8_WAIT_V(8); PG8_WAIT_L(0); PG8_BAR; PG8_MMA(0, 0, At, B0); PG8_MMA(0, 1, At, B1); PG8_BAR; PG8_SCHED;
;             PG8_LDA1(At, 1); PG8_STAGE(PG8_SB(1, 0), b3); PG8_STAGE(PG8_SB(1, 1), b3 + hstep); PG8_STAGE(PG8_SA(1, 0), a3);
;             PG8_WAIT_V(8); PG8_WAIT_L(0); PG8_BAR; PG8_MMA1(At, B0, B1); PG8_BAR; PG8_SCHED;
	s_mov_b32 m0, s86
	v_lshl_add_u64 v[82:83], v[226:227], 0, s[94:95]
	s_add_u32 s38, s38, 0x40080
	s_nop 0
	ds_read_b128 v[66:69], v190 offset:49152
	ds_read_b128 v[70:73], v190 offset:50176
	ds_read_b128 v[200:203], v190 offset:51200
	ds_read_b128 v[204:207], v190 offset:52224
	ds_read_b128 v[214:217], v190 offset:53248
	ds_read_b128 v[218:221], v190 offset:54272
	ds_read_b128 v[222:225], v190 offset:55296
	ds_read_b128 v[230:233], v190 offset:56320
	global_load_lds_dwordx4 v[82:83], off
	v_lshl_add_u64 v[82:83], v[238:239], 0, s[94:95]
	s_mov_b32 m0, s87
	s_addc_u32 s39, s39, 0
	global_load_lds_dwordx4 v[82:83], off
	v_lshl_add_u64 v[82:83], s[38:39], 0, v[164:165]
	s_mov_b32 m0, s8
	s_nop 0
	global_load_lds_dwordx4 v[82:83], off
	v_lshl_add_u64 v[82:83], s[38:39], 0, v[166:167]
	s_mov_b32 m0, s9
	s_nop 0
	global_load_lds_dwordx4 v[82:83], off
	v_lshl_add_u64 v[82:83], v[248:249], 0, s[94:95]
	s_mov_b32 m0, s76
	s_nop 0
	global_load_lds_dwordx4 v[82:83], off
	v_lshl_add_u64 v[82:83], v[210:211], 0, s[94:95]
	s_mov_b32 m0, s48
	s_nop 0
	global_load_lds_dwordx4 v[82:83], off
	s_waitcnt vmcnt(8)
	s_waitcnt lgkmcnt(0)
	s_barrier
	s_waitcnt lgkmcnt(0)
	v_mfma_f32_16x16x32_f16 v[82:85], v[50:53], v[66:69], v[94:97]
	v_mfma_f32_16x16x32_f16 v[94:97], v[54:57], v[70:73], v[82:85]
	v_mfma_f32_16x16x32_f16 v[82:85], v[58:61], v[66:69], v[90:93]
	v_mfma_f32_16x16x32_f16 v[78:81], v[50:53], v[200:203], v[78:81]
	v_mfma_f32_16x16x32_f16 v[74:77], v[58:61], v[200:203], v[74:77]
	v_mfma_f32_16x16x32_f16 v[46:49], v[50:53], v[214:217], v[46:49]
	v_mfma_f32_16x16x32_f16 v[42:45], v[58:61], v[214:217], v[42:45]
	v_mfma_f32_16x16x32_f16 v[14:17], v[50:53], v[222:225], v[14:17]
	v_mfma_f32_16x16x32_f16 v[10:13], v[58:61], v[222:225], v[10:13]
	s_add_i32 s97, s97, 2
	v_mfma_f32_16x16x32_f16 v[90:93], v[62:65], v[70:73], v[82:85]
	v_mfma_f32_16x16x32_f16 v[78:81], v[54:57], v[204:207], v[78:81]
	v_mfma_f32_16x16x32_f16 v[74:77], v[62:65], v[204:207], v[74:77]
	v_mfma_f32_16x16x32_f16 v[46:49], v[54:57], v[218:221], v[46:49]
	v_mfma_f32_16x16x32_f16 v[42:45], v[62:65], v[218:221], v[42:45]
	v_mfma_f32_16x16x32_f16 v[14:17], v[54:57], v[230:233], v[14:17]
	s_add_u32 s2, s2, 0x100
	s_addc_u32 s3, s3, 0
	v_mfma_f32_16x16x32_f16 v[10:13], v[62:65], v[230:233], v[10:13]
	v_mfma_f32_16x16x32_f16 v[18:21], v[172:175], v[66:69], v[18:21]
	v_mfma_f32_16x16x32_f16 v[86:89], v[176:179], v[70:73], v[18:21]
	v_mfma_f32_16x16x32_f16 v[18:21], v[192:195], v[66:69], v[22:25]
	v_mfma_f32_16x16x32_f16 v[82:85], v[196:199], v[70:73], v[18:21]
	v_mfma_f32_16x16x32_f16 v[18:21], v[172:175], v[200:203], v[26:29]
	s_add_u32 s44, s44, 0x100
	s_addc_u32 s45, s45, 0
	v_mfma_f32_16x16x32_f16 v[70:73], v[176:179], v[204:207], v[18:21]
	v_mfma_f32_16x16x32_f16 v[18:21], v[192:195], v[200:203], v[30:33]
	v_mfma_f32_16x16x32_f16 v[66:69], v[196:199], v[204:207], v[18:21]
	v_mfma_f32_16x16x32_f16 v[18:21], v[172:175], v[214:217], v[38:41]
	v_mfma_f32_16x16x32_f16 v[38:41], v[176:179], v[218:221], v[18:21]
	v_mfma_f32_16x16x32_f16 v[18:21], v[192:195], v[214:217], v[34:37]
	v_mfma_f32_16x16x32_f16 v[6:9], v[172:175], v[222:225], v[6:9]
	v_mfma_f32_16x16x32_f16 v[2:5], v[192:195], v[222:225], v[2:5]
	v_mfma_f32_16x16x32_f16 v[34:37], v[196:199], v[218:221], v[18:21]
	v_mfma_f32_16x16x32_f16 v[6:9], v[176:179], v[230:233], v[6:9]
	v_mfma_f32_16x16x32_f16 v[2:5], v[196:199], v[230:233], v[2:5]
	s_barrier
	s_cmp_gt_u32 s97, 13
	s_cbranch_scc0 .LBB0_452
	s_and_b64 vcc, exec, s[14:15]
	s_cbranch_vccz .LBB0_455
	s_barrier

; #define PG8_STAGE(bufoff, gbase) do { _Pragma("unroll") for (int _i = 0; _i < 2; ++_i) \
;         __builtin_amdgcn_global_load_lds((const unsigned*)((const char*)(gbase) + voffA[_i]), (LAS unsigned*)(lds + (bufoff) + ldsw + _i * 8192), 16, 0, 0); } while (0)
; #define PG8_LDA(dst, b, h) do { _Pragma("unroll") for (int m = 0; m < 4; ++m) _Pragma("unroll") for (int k = 0; k < 2; ++k) dst[m][k] = *(const LAS h16x8*)(lds + PG8_SA(b, h) + aoff + m * 2048 + k * 1024); } while (0)
; #define PG8_LDB(dst, b, h) do { _Pragma("unroll") for (int n = 0; n < 2; ++n) _Pragma("unroll") for (int k = 0; k < 2; ++k) dst[n][k] = *(const LAS h16x8*)(lds + PG8_SB(b, h) + boff + n * 2048 + k * 1024); } while (0)
; #define PG8_LDA1(dst, b) do { if constexpr (!HALFM) PG8_LDA(dst, b, 1); } while (0)
; #define PG8_MMA1(At, B0, B1) do { if constexpr (!HALFM) { PG8_MMA(1, 0, At, B0); PG8_MMA(1, 1, At, B1); } } while (0)
; #define PG8_WAIT_V(n) asm volatile("s_waitcnt vmcnt(" #n ")" ::: "memory")
; #define PG8_WAIT_L(n) asm volatile("s_waitcnt lgkmcnt(" #n ")" ::: "memory")
; #define PG8_BAR __builtin_amdgcn_s_barrier()
; #define PG8_SCHED __builtin_amdgcn_sched_barrier(0)
; template <class Epi, bool ALIGN_EPI, bool SP2, bool BF = false, bool HALFM = false, class Order = StaticOrder>
; __device__ __forceinline__ void gemm_phase(LAS unsigned char* lds, const int tid, const Gemm g, const Order& S, const Epi& E, const bool dry = false) {
;     ...
;             if constexpr (SP2) {
;             PG8_LDB(B0, 0, 0); PG8_LDB(B1, 0, 1); PG8_SCHED; PG8_LDA(At, 0, 0); PG8_STAGE(PG8_SA(1, 1), a1 + hstep);
;             PG8_WAIT_V(8); PG8_WAIT_L(0); PG8_BAR; PG8_MMA(0, 0, At, B0); PG8_MMA(0, 1, At, B1); PG8_BAR; PG8_SCHED;
;             PG8_LDA1(At, 0); PG8_STAGE(PG8_SB(0, 0), b2); PG8_STAGE(PG8_SB(0, 1), b2 + hstep); PG8_STAGE(PG8_SA(0, 0), a2);
;             PG8_WAIT_V(8); PG8_WAIT_L(0); PG8_BAR; PG8_MMA1(At, B0, B1); PG8_BAR; PG8_SCHED;
.LBB0_561:
	v_add_u32_e32 v144, s46, v198
	v_add_u32_e32 v160, s49, v198
	ds_read_b128 v[132:135], v144
	ds_read_b128 v[136:139], v144 offset:1024
	ds_read_b128 v[140:143], v144 offset:2048
	ds_read_b128 v[144:147], v144 offset:3072
	ds_read_b128 v[148:151], v160
	ds_read_b128 v[152:155], v160 offset:1024
	ds_read_b128 v[156:159], v160 offset:2048
	ds_read_b128 v[160:163], v160 offset:3072
	s_add_u32 s38, s36, 0xfffc0080
	s_addc_u32 s39, s37, -1
	s_cmp_eq_u32 s21, 12
	s_cselect_b32 s43, s3, s39
	s_cselect_b32 s42, s5, s38
	s_cselect_b32 s39, s8, s19
	s_cselect_b32 s38, s9, s11
	v_lshl_add_u64 v[194:195], s[36:37], 0, v[168:169]
	s_add_i32 m0, s52, 0xc000
	ds_read_b128 v[170:173], v199
	ds_read_b128 v[174:177], v199 offset:1024
	ds_read_b128 v[178:181], v199 offset:2048
	ds_read_b128 v[182:185], v199 offset:3072
	ds_read_b128 v[186:189], v199 offset:4096
	ds_read_b128 v[190:193], v199 offset:5120
	ds_read_b128 v[200:203], v199 offset:6144
	ds_read_b128 v[204:207], v199 offset:7168
	global_load_lds_dwordx4 v[194:195], off
	v_lshl_add_u64 v[194:195], s[36:37], 0, v[166:167]
	s_add_i32 m0, s52, 0xe000
	s_nop 0
	global_load_lds_dwordx4 v[194:195], off
	s_waitcnt vmcnt(8)
	s_waitcnt lgkmcnt(0)
	s_barrier
	s_waitcnt lgkmcnt(0)
	v_mfma_f32_16x16x32_f16 v[70:73], v[132:135], v[170:173], v[70:73]
	v_mfma_f32_16x16x32_f16 v[66:69], v[140:143], v[170:173], v[66:69]
	v_mfma_f32_16x16x32_f16 v[50:53], v[132:135], v[178:181], v[50:53]
	v_mfma_f32_16x16x32_f16 v[46:49], v[140:143], v[178:181], v[46:49]
	v_mfma_f32_16x16x32_f16 v[54:57], v[132:135], v[186:189], v[54:57]
	v_mfma_f32_16x16x32_f16 v[42:45], v[140:143], v[186:189], v[42:45]
	v_mfma_f32_16x16x32_f16 v[38:41], v[132:135], v[200:203], v[38:41]
	v_mfma_f32_16x16x32_f16 v[34:37], v[140:143], v[200:203], v[34:37]
	v_mfma_f32_16x16x32_f16 v[70:73], v[136:139], v[174:177], v[70:73]
	v_mfma_f32_16x16x32_f16 v[66:69], v[144:147], v[174:177], v[66:69]
	v_mfma_f32_16x16x32_f16 v[50:53], v[136:139], v[182:185], v[50:53]
	v_mfma_f32_16x16x32_f16 v[46:49], v[144:147], v[182:185], v[46:49]
	v_mfma_f32_16x16x32_f16 v[54:57], v[136:139], v[190:193], v[54:57]
	v_mfma_f32_16x16x32_f16 v[42:45], v[144:147], v[190:193], v[42:45]
	v_mfma_f32_16x16x32_f16 v[38:41], v[136:139], v[204:207], v[38:41]
	v_mfma_f32_16x16x32_f16 v[34:37], v[144:147], v[204:207], v[34:37]
	v_mfma_f32_16x16x32_f16 v[126:129], v[148:151], v[170:173], v[126:129]
	v_mfma_f32_16x16x32_f16 v[122:125], v[156:159], v[170:173], v[122:125]
	v_mfma_f32_16x16x32_f16 v[118:121], v[148:151], v[178:181], v[118:121]
	v_mfma_f32_16x16x32_f16 v[114:117], v[156:159], v[178:181], v[114:117]
	v_mfma_f32_16x16x32_f16 v[110:113], v[148:151], v[186:189], v[110:113]
	v_mfma_f32_16x16x32_f16 v[106:109], v[156:159], v[186:189], v[106:109]
	v_mfma_f32_16x16x32_f16 v[102:105], v[148:151], v[200:203], v[102:105]
	v_mfma_f32_16x16x32_f16 v[98:101], v[156:159], v[200:203], v[98:101]
	v_mfma_f32_16x16x32_f16 v[126:129], v[152:155], v[174:177], v[126:129]
	v_mfma_f32_16x16x32_f16 v[122:125], v[160:163], v[174:177], v[122:125]
	v_mfma_f32_16x16x32_f16 v[118:121], v[152:155], v[182:185], v[118:121]
	v_mfma_f32_16x16x32_f16 v[114:117], v[160:163], v[182:185], v[114:117]
	v_mfma_f32_16x16x32_f16 v[110:113], v[152:155], v[190:193], v[110:113]
	v_mfma_f32_16x16x32_f16 v[106:109], v[160:163], v[190:193], v[106:109]
	v_mfma_f32_16x16x32_f16 v[102:105], v[152:155], v[204:207], v[102:105]
	v_mfma_f32_16x16x32_f16 v[98:101], v[160:163], v[204:207], v[98:101]
	s_barrier
	s_mov_b32 m0, s47
	v_lshl_add_u64 v[194:195], s[38:39], 0, v[0:1]
	s_add_u32 vcc_lo, s38, 0x40000
	ds_read_b128 v[170:173], v199 offset:16384
	ds_read_b128 v[174:177], v199 offset:17408
	ds_read_b128 v[178:181], v199 offset:18432
	ds_read_b128 v[182:185], v199 offset:19456
	ds_read_b128 v[186:189], v199 offset:20480
	ds_read_b128 v[190:193], v199 offset:21504
	ds_read_b128 v[200:203], v199 offset:22528
	ds_read_b128 v[204:207], v199 offset:23552
	global_load_lds_dwordx4 v[194:195], off
	v_lshl_add_u64 v[214:215], s[38:39], 0, v[164:165]
	s_mov_b32 m0, s48
	s_addc_u32 vcc_hi, s39, 0
	global_load_lds_dwordx4 v[214:215], off
	v_lshl_add_u64 v[216:217], vcc, 0, v[0:1]
	s_mov_b32 m0, s50
	v_lshl_add_u64 v[218:219], s[42:43], 0, v[164:165]
	global_load_lds_dwordx4 v[216:217], off
	v_lshl_add_u64 v[216:217], vcc, 0, v[164:165]
	s_mov_b32 m0, s51
	s_nop 0
	global_load_lds_dwordx4 v[216:217], off
	v_lshl_add_u64 v[216:217], s[42:43], 0, v[0:1]
	s_mov_b32 m0, s52
	s_nop 0
	global_load_lds_dwordx4 v[216:217], off
	s_mov_b32 m0, s53
	s_nop 0
	global_load_lds_dwordx4 v[218:219], off
	s_waitcnt vmcnt(8)
	s_waitcnt lgkmcnt(0)
	s_barrier
; #define PG8_STAGE(bufoff, gbase) do { _Pragma("unroll") for (int _i = 0; _i < 2; ++_i) \
;         __builtin_amdgcn_global_load_lds((const unsigned*)((const char*)(gbase) + voffA[_i]), (LAS unsigned*)(lds + (bufoff) + ldsw + _i * 8192), 16, 0, 0); } while (0)
; #define PG8_LDA(dst, b, h) do { _Pragma("unroll") for (int m = 0; m < 4; ++m) _Pragma("unroll") for (int k = 0; k < 2; ++k) dst[m][k] = *(const LAS h16x8*)(lds + PG8_SA(b, h) + aoff + m * 2048 + k * 1024); } while (0)
; #define PG8_LDB(dst, b, h) do { _Pragma("unroll") for (int n = 0; n < 2; ++n) _Pragma("unroll") for (int k = 0; k < 2; ++k) dst[n][k] = *(const LAS h16x8*)(lds + PG8_SB(b, h) + boff + n * 2048 + k * 1024); } while (0)
; #define PG8_MMA1(At, B0, B1) do { if constexpr (!HALFM) { PG8_MMA(1, 0, At, B0); PG8_MMA(1, 1, At, B1); } } while (0)
; #define PG8_WAIT_V(n) asm volatile("s_waitcnt vmcnt(" #n ")" ::: "memory")
; #define PG8_WAIT_L(n) asm volatile("s_waitcnt lgkmcnt(" #n ")" ::: "memory")
; #define PG8_BAR __builtin_amdgcn_s_barrier()
; #define PG8_SCHED __builtin_amdgcn_sched_barrier(0)
; template <class Epi, bool ALIGN_EPI, bool SP2, bool BF = false, bool HALFM = false, class Order = StaticOrder>
; __device__ __forceinline__ void gemm_phase(LAS unsigned char* lds, const int tid, const Gemm g, const Order& S, const Epi& E, const bool dry = false) {
;     ...
;             PG8_WAIT_V(8); PG8_WAIT_L(0); PG8_BAR; PG8_MMA1(At, B0, B1); PG8_BAR; PG8_SCHED;
;             PG8_LDB(B0, 1, 0); PG8_LDB(B1, 1, 1); PG8_SCHED; PG8_LDA(At, 1, 0); PG8_STAGE(PG8_SA(0, 1), a2 + hstep);
;             PG8_WAIT_V(8); PG8_WAIT_L(0); PG8_BAR; PG8_MMA(0, 0, At, B0); PG8_MMA(0, 1, At, B1); PG8_BAR; PG8_SCHED;
	s_waitcnt lgkmcnt(0)
	v_mfma_f32_16x16x32_f16 v[30:33], v[132:135], v[170:173], v[30:33]
	v_mfma_f32_16x16x32_f16 v[26:29], v[140:143], v[170:173], v[26:29]
	v_mfma_f32_16x16x32_f16 v[22:25], v[132:135], v[178:181], v[22:25]
	v_mfma_f32_16x16x32_f16 v[18:21], v[140:143], v[178:181], v[18:21]
	v_mfma_f32_16x16x32_f16 v[14:17], v[132:135], v[186:189], v[14:17]
	v_mfma_f32_16x16x32_f16 v[10:13], v[140:143], v[186:189], v[10:13]
	v_mfma_f32_16x16x32_f16 v[6:9], v[132:135], v[200:203], v[6:9]
	v_mfma_f32_16x16x32_f16 v[2:5], v[140:143], v[200:203], v[2:5]
	v_mfma_f32_16x16x32_f16 v[30:33], v[136:139], v[174:177], v[30:33]
	v_mfma_f32_16x16x32_f16 v[26:29], v[144:147], v[174:177], v[26:29]
	v_mfma_f32_16x16x32_f16 v[22:25], v[136:139], v[182:185], v[22:25]
	v_mfma_f32_16x16x32_f16 v[18:21], v[144:147], v[182:185], v[18:21]
	v_mfma_f32_16x16x32_f16 v[14:17], v[136:139], v[190:193], v[14:17]
	v_mfma_f32_16x16x32_f16 v[10:13], v[144:147], v[190:193], v[10:13]
	v_mfma_f32_16x16x32_f16 v[6:9], v[136:139], v[204:207], v[6:9]
	v_mfma_f32_16x16x32_f16 v[2:5], v[144:147], v[204:207], v[2:5]
	v_mfma_f32_16x16x32_f16 v[94:97], v[148:151], v[170:173], v[94:97]
	v_mfma_f32_16x16x32_f16 v[90:93], v[156:159], v[170:173], v[90:93]
	v_mfma_f32_16x16x32_f16 v[86:89], v[148:151], v[178:181], v[86:89]
	v_mfma_f32_16x16x32_f16 v[82:85], v[156:159], v[178:181], v[82:85]
	v_mfma_f32_16x16x32_f16 v[78:81], v[148:151], v[186:189], v[78:81]
	v_mfma_f32_16x16x32_f16 v[74:77], v[156:159], v[186:189], v[74:77]
	v_mfma_f32_16x16x32_f16 v[62:65], v[148:151], v[200:203], v[62:65]
	v_mfma_f32_16x16x32_f16 v[58:61], v[156:159], v[200:203], v[58:61]
	v_mfma_f32_16x16x32_f16 v[94:97], v[152:155], v[174:177], v[94:97]
	v_mfma_f32_16x16x32_f16 v[90:93], v[160:163], v[174:177], v[90:93]
	v_mfma_f32_16x16x32_f16 v[86:89], v[152:155], v[182:185], v[86:89]
	v_mfma_f32_16x16x32_f16 v[82:85], v[160:163], v[182:185], v[82:85]
	v_mfma_f32_16x16x32_f16 v[78:81], v[152:155], v[190:193], v[78:81]
	v_mfma_f32_16x16x32_f16 v[74:77], v[160:163], v[190:193], v[74:77]
	v_mfma_f32_16x16x32_f16 v[62:65], v[152:155], v[204:207], v[62:65]
	v_mfma_f32_16x16x32_f16 v[58:61], v[160:163], v[204:207], v[58:61]
	s_barrier
	v_add_u32_e32 v144, s79, v198
	v_add_u32_e32 v160, s84, v198
	ds_read_b128 v[132:135], v144
	ds_read_b128 v[136:139], v144 offset:1024
	ds_read_b128 v[140:143], v144 offset:2048
	ds_read_b128 v[144:147], v144 offset:3072
	ds_read_b128 v[148:151], v160
	ds_read_b128 v[152:155], v160 offset:1024
	ds_read_b128 v[156:159], v160 offset:2048
	ds_read_b128 v[160:163], v160 offset:3072
	s_add_u32 s42, s42, 0x40000
	s_addc_u32 s43, s43, 0
	s_mov_b32 m0, s54
	v_lshl_add_u64 v[220:221], s[42:43], 0, v[0:1]
	ds_read_b128 v[170:173], v199 offset:32768
	ds_read_b128 v[174:177], v199 offset:33792
	ds_read_b128 v[178:181], v199 offset:34816
	ds_read_b128 v[182:185], v199 offset:35840
	ds_read_b128 v[186:189], v199 offset:36864
	ds_read_b128 v[190:193], v199 offset:37888
	ds_read_b128 v[200:203], v199 offset:38912
	ds_read_b128 v[204:207], v199 offset:39936
	global_load_lds_dwordx4 v[220:221], off
	v_lshl_add_u64 v[220:221], s[42:43], 0, v[164:165]
	s_mov_b32 m0, s55
	s_nop 0
	global_load_lds_dwordx4 v[220:221], off
	s_waitcnt vmcnt(8)
	s_waitcnt lgkmcnt(0)
	s_barrier
	s_waitcnt lgkmcnt(0)
	v_mfma_f32_16x16x32_f16 v[70:73], v[132:135], v[170:173], v[70:73]
	v_mfma_f32_16x16x32_f16 v[66:69], v[140:143], v[170:173], v[66:69]
	v_mfma_f32_16x16x32_f16 v[50:53], v[132:135], v[178:181], v[50:53]
	v_mfma_f32_16x16x32_f16 v[46:49], v[140:143], v[178:181], v[46:49]
	v_mfma_f32_16x16x32_f16 v[54:57], v[132:135], v[186:189], v[54:57]
	v_mfma_f32_16x16x32_f16 v[42:45], v[140:143], v[186:189], v[42:45]
	v_mfma_f32_16x16x32_f16 v[38:41], v[132:135], v[200:203], v[38:41]
	v_mfma_f32_16x16x32_f16 v[34:37], v[140:143], v[200:203], v[34:37]
	v_mfma_f32_16x16x32_f16 v[70:73], v[136:139], v[174:177], v[70:73]
	v_mfma_f32_16x16x32_f16 v[66:69], v[144:147], v[174:177], v[66:69]
	v_mfma_f32_16x16x32_f16 v[50:53], v[136:139], v[182:185], v[50:53]
	v_mfma_f32_16x16x32_f16 v[46:49], v[144:147], v[182:185], v[46:49]
	v_mfma_f32_16x16x32_f16 v[54:57], v[136:139], v[190:193], v[54:57]
	v_mfma_f32_16x16x32_f16 v[42:45], v[144:147], v[190:193], v[42:45]
	v_mfma_f32_16x16x32_f16 v[38:41], v[136:139], v[204:207], v[38:41]
	v_mfma_f32_16x16x32_f16 v[34:37], v[144:147], v[204:207], v[34:37]
	v_mfma_f32_16x16x32_f16 v[126:129], v[148:151], v[170:173], v[126:129]
	v_mfma_f32_16x16x32_f16 v[122:125], v[156:159], v[170:173], v[122:125]
	v_mfma_f32_16x16x32_f16 v[118:121], v[148:151], v[178:181], v[118:121]
	v_mfma_f32_16x16x32_f16 v[114:117], v[156:159], v[178:181], v[114:117]
	v_mfma_f32_16x16x32_f16 v[110:113], v[148:151], v[186:189], v[110:113]
	v_mfma_f32_16x16x32_f16 v[106:109], v[156:159], v[186:189], v[106:109]
	v_mfma_f32_16x16x32_f16 v[102:105], v[148:151], v[200:203], v[102:105]
	v_mfma_f32_16x16x32_f16 v[98:101], v[156:159], v[200:203], v[98:101]
	v_mfma_f32_16x16x32_f16 v[126:129], v[152:155], v[174:177], v[126:129]
	v_mfma_f32_16x16x32_f16 v[122:125], v[160:163], v[174:177], v[122:125]
	v_mfma_f32_16x16x32_f16 v[118:121], v[152:155], v[182:185], v[118:121]
	v_mfma_f32_16x16x32_f16 v[114:117], v[160:163], v[182:185], v[114:117]
	v_mfma_f32_16x16x32_f16 v[110:113], v[152:155], v[190:193], v[110:113]
	v_mfma_f32_16x16x32_f16 v[106:109], v[160:163], v[190:193], v[106:109]
	v_mfma_f32_16x16x32_f16 v[102:105], v[152:155], v[204:207], v[102:105]
	v_mfma_f32_16x16x32_f16 v[98:101], v[160:163], v[204:207], v[98:101]
	s_barrier
; #define PG8_STAGE(bufoff, gbase) do { _Pragma("unroll") for (int _i = 0; _i < 2; ++_i) \
;         __builtin_amdgcn_global_load_lds((const unsigned*)((const char*)(gbase) + voffA[_i]), (LAS unsigned*)(lds + (bufoff) + ldsw + _i * 8192), 16, 0, 0); } while (0)
; #define PG8_LDA1(dst, b) do { if constexpr (!HALFM) PG8_LDA(dst, b, 1); } while (0)
; #define PG8_MMA1(At, B0, B1) do { if constexpr (!HALFM) { PG8_MMA(1, 0, At, B0); PG8_MMA(1, 1, At, B1); } } while (0)
; #define PG8_WAIT_V(n) asm volatile("s_waitcnt vmcnt(" #n ")" ::: "memory")
; #define PG8_WAIT_L(n) asm volatile("s_waitcnt lgkmcnt(" #n ")" ::: "memory")
; #define PG8_BAR __builtin_amdgcn_s_barrier()
; #define PG8_SCHED __builtin_amdgcn_sched_barrier(0)
; template <class Epi, bool ALIGN_EPI, bool SP2, bool BF = false, bool HALFM = false, class Order = StaticOrder>
; __device__ __forceinline__ void gemm_phase(LAS unsigned char* lds, const int tid, const Gemm g, const Order& S, const Epi& E, const bool dry = false) {
;     ...
;             PG8_WAIT_V(8); PG8_WAIT_L(0); PG8_BAR; PG8_MMA(0, 0, At, B0); PG8_MMA(0, 1, At, B1); PG8_BAR; PG8_SCHED;
;             PG8_LDA1(At, 1); PG8_STAGE(PG8_SB(1, 0), b3); PG8_STAGE(PG8_SB(1, 1), b3 + hstep); PG8_STAGE(PG8_SA(1, 0), a3);
;             PG8_WAIT_V(8); PG8_WAIT_L(0); PG8_BAR; PG8_MMA1(At, B0, B1); PG8_BAR; PG8_SCHED;
	s_mov_b32 m0, s80
	v_lshl_add_u64 v[194:195], v[194:195], 0, s[94:95]
	s_add_u32 s38, s38, 0x40080
	ds_read_b128 v[170:173], v199 offset:49152
	ds_read_b128 v[174:177], v199 offset:50176
	ds_read_b128 v[178:181], v199 offset:51200
	ds_read_b128 v[182:185], v199 offset:52224
	ds_read_b128 v[186:189], v199 offset:53248
	ds_read_b128 v[190:193], v199 offset:54272
	ds_read_b128 v[200:203], v199 offset:55296
	ds_read_b128 v[204:207], v199 offset:56320
	global_load_lds_dwordx4 v[194:195], off
	v_lshl_add_u64 v[194:195], v[214:215], 0, s[94:95]
	s_mov_b32 m0, s81
	s_addc_u32 s39, s39, 0
	global_load_lds_dwordx4 v[194:195], off
	v_lshl_add_u64 v[194:195], s[38:39], 0, v[0:1]
	s_mov_b32 m0, s85
	s_nop 0
	global_load_lds_dwordx4 v[194:195], off
	v_lshl_add_u64 v[194:195], s[38:39], 0, v[164:165]
	s_mov_b32 m0, s86
	s_nop 0
	global_load_lds_dwordx4 v[194:195], off
	v_lshl_add_u64 v[194:195], v[216:217], 0, s[94:95]
	s_mov_b32 m0, s82
	s_nop 0
	global_load_lds_dwordx4 v[194:195], off
	v_lshl_add_u64 v[194:195], v[218:219], 0, s[94:95]
	s_mov_b32 m0, s83
	s_nop 0
	global_load_lds_dwordx4 v[194:195], off
	s_waitcnt vmcnt(8)
	s_waitcnt lgkmcnt(0)
	s_barrier
	s_waitcnt lgkmcnt(0)
	v_mfma_f32_16x16x32_f16 v[30:33], v[132:135], v[170:173], v[30:33]
	v_mfma_f32_16x16x32_f16 v[26:29], v[140:143], v[170:173], v[26:29]
	v_mfma_f32_16x16x32_f16 v[22:25], v[132:135], v[178:181], v[22:25]
	v_mfma_f32_16x16x32_f16 v[18:21], v[140:143], v[178:181], v[18:21]
	v_mfma_f32_16x16x32_f16 v[14:17], v[132:135], v[186:189], v[14:17]
	v_mfma_f32_16x16x32_f16 v[10:13], v[140:143], v[186:189], v[10:13]
	v_mfma_f32_16x16x32_f16 v[6:9], v[132:135], v[200:203], v[6:9]
	v_mfma_f32_16x16x32_f16 v[2:5], v[140:143], v[200:203], v[2:5]
	v_mfma_f32_16x16x32_f16 v[30:33], v[136:139], v[174:177], v[30:33]
	s_add_i32 s21, s21, 2
	v_mfma_f32_16x16x32_f16 v[26:29], v[144:147], v[174:177], v[26:29]
	v_mfma_f32_16x16x32_f16 v[22:25], v[136:139], v[182:185], v[22:25]
	v_mfma_f32_16x16x32_f16 v[18:21], v[144:147], v[182:185], v[18:21]
	v_mfma_f32_16x16x32_f16 v[14:17], v[136:139], v[190:193], v[14:17]
	v_mfma_f32_16x16x32_f16 v[10:13], v[144:147], v[190:193], v[10:13]
	v_mfma_f32_16x16x32_f16 v[6:9], v[136:139], v[204:207], v[6:9]
	s_add_u32 s11, s11, 0x100
	s_addc_u32 s19, s19, 0
	v_mfma_f32_16x16x32_f16 v[2:5], v[144:147], v[204:207], v[2:5]
	v_mfma_f32_16x16x32_f16 v[94:97], v[148:151], v[170:173], v[94:97]
	v_mfma_f32_16x16x32_f16 v[90:93], v[156:159], v[170:173], v[90:93]
	v_mfma_f32_16x16x32_f16 v[86:89], v[148:151], v[178:181], v[86:89]
	v_mfma_f32_16x16x32_f16 v[82:85], v[156:159], v[178:181], v[82:85]
	v_mfma_f32_16x16x32_f16 v[78:81], v[148:151], v[186:189], v[78:81]
	s_add_u32 s36, s36, 0x100
	s_addc_u32 s37, s37, 0
	v_mfma_f32_16x16x32_f16 v[74:77], v[156:159], v[186:189], v[74:77]
	v_mfma_f32_16x16x32_f16 v[62:65], v[148:151], v[200:203], v[62:65]
	v_mfma_f32_16x16x32_f16 v[58:61], v[156:159], v[200:203], v[58:61]
	v_mfma_f32_16x16x32_f16 v[94:97], v[152:155], v[174:177], v[94:97]
	v_mfma_f32_16x16x32_f16 v[90:93], v[160:163], v[174:177], v[90:93]
	v_mfma_f32_16x16x32_f16 v[86:89], v[152:155], v[182:185], v[86:89]
	v_mfma_f32_16x16x32_f16 v[82:85], v[160:163], v[182:185], v[82:85]
	v_mfma_f32_16x16x32_f16 v[78:81], v[152:155], v[190:193], v[78:81]
	v_mfma_f32_16x16x32_f16 v[74:77], v[160:163], v[190:193], v[74:77]
	v_mfma_f32_16x16x32_f16 v[62:65], v[152:155], v[204:207], v[62:65]
	v_mfma_f32_16x16x32_f16 v[58:61], v[160:163], v[204:207], v[58:61]
	s_barrier
	s_cmp_gt_u32 s21, 13
	s_cbranch_scc0 .LBB0_561
	s_and_b64 vcc, exec, s[12:13]
	s_cbranch_vccz .LBB0_564
	s_barrier
